# FFN-up SwiGLU epilogue rewritten by hand: fewer VALU ops (rstd folded into exp argument and reciprocal), no hazard nops, scalar-base stores
# speedup vs baseline: 1.0134x; 1.0080x over previous
; __device__ __forceinline__ unsigned pk(float lo, float hi) { f32x2v v = {lo, hi}; bf16x2v b = __builtin_convertvector(v, bf16x2v); return __builtin_bit_cast(unsigned, b); }
; __device__ __forceinline__ float silu_f(float x) { return x * __builtin_amdgcn_rcpf(1.0f + __builtin_amdgcn_exp2f(-1.4426950408889634f * x)); }
; __device__ __forceinline__ void rstd8(const float* part, int row0, float (&rs)[2][4]) {
;     f32x4 v[2][4];
; #pragma unroll
;     for (int ai = 0; ai < 2; ++ai)
; #pragma unroll
;         for (int m = 0; m < 4; ++m) v[ai][m] = *(const f32x4*)(part + (size_t)(row0 + ai * HALF + m * 16) * 4);
; #pragma unroll
;     for (int ai = 0; ai < 2; ++ai)
; #pragma unroll
;         for (int m = 0; m < 4; ++m) rs[ai][m] = __builtin_amdgcn_rsqf(((v[ai][m][0] + v[ai][m][1]) + (v[ai][m][2] + v[ai][m][3])) * (1.0f / 1024.0f) + 1e-6f);
;     __device__ __forceinline__ void operator()(const f32x4 (&acc)[2][2][4][2], const Unit& u, int wr, int wc, int fr, int fq) const {
;         const int row0 = u.pm * BM + wr * 64 + fr, col0 = u.pn * 128 + wc * 32 + 8 * fq;
;         float rsv[2][4]; rstd8(part, row0, rsv);
; #pragma unroll
;         for (int ai = 0; ai < 2; ++ai)
; #pragma unroll
;             for (int m = 0; m < 4; ++m) { const int row = row0 + ai * HALF + m * 16; const float rs = rsv[ai][m];
;                 const f32x4 g0 = acc[ai][0][m][0] * rs, g1 = acc[ai][0][m][1] * rs, u0 = acc[ai][1][m][0] * rs, u1 = acc[ai][1][m][1] * rs;
;                 u32x4 w; w.x = pk(silu_f(g0[0]) * u0[0], silu_f(g0[1]) * u0[1]); w.y = pk(silu_f(g0[2]) * u0[2], silu_f(g0[3]) * u0[3]);
;                 w.z = pk(silu_f(g1[0]) * u1[0], silu_f(g1[1]) * u1[1]); w.w = pk(silu_f(g1[2]) * u1[2], silu_f(g1[3]) * u1[3]);
;                 *(u32x4*)(H + (size_t)row * DFF + col0) = w; }
.LBB0_320:
	v_lshl_add_u32 v166, s50, 8, v145
	v_ashrrev_i32_e32 v167, 31, v166
	v_lshl_add_u64 v[140:141], v[166:167], 4, s[14:15]
	v_or_b32_e32 v162, 16, v166
	global_load_dwordx4 v[170:173], v[140:141], off
	v_ashrrev_i32_e32 v163, 31, v162
	v_lshl_add_u64 v[140:141], v[162:163], 4, s[14:15]
	v_or_b32_e32 v158, 32, v166
	global_load_dwordx4 v[174:177], v[140:141], off
	v_ashrrev_i32_e32 v159, 31, v158
	v_lshl_add_u64 v[140:141], v[158:159], 4, s[14:15]
	v_or_b32_e32 v154, 48, v166
	global_load_dwordx4 v[178:181], v[140:141], off
	v_ashrrev_i32_e32 v155, 31, v154
	v_lshl_add_u64 v[140:141], v[154:155], 4, s[14:15]
	v_add_u32_e32 v150, 0x80, v166
	global_load_dwordx4 v[182:185], v[140:141], off
	v_ashrrev_i32_e32 v151, 31, v150
	v_lshl_add_u64 v[140:141], v[150:151], 4, s[14:15]
	v_add_u32_e32 v146, 0x90, v166
	global_load_dwordx4 v[186:189], v[140:141], off
	v_ashrrev_i32_e32 v147, 31, v146
	v_add_u32_e32 v142, 0xa0, v166
	v_lshl_add_u64 v[140:141], v[146:147], 4, s[14:15]
	v_ashrrev_i32_e32 v143, 31, v142
	global_load_dwordx4 v[190:193], v[140:141], off
	v_lshl_add_u64 v[140:141], v[142:143], 4, s[14:15]
	global_load_dwordx4 v[204:207], v[140:141], off
	v_add_u32_e32 v140, 0xb0, v166
	v_ashrrev_i32_e32 v141, 31, v140
	v_lshl_add_u64 v[160:161], v[140:141], 4, s[14:15]
	global_load_dwordx4 v[208:211], v[160:161], off
	v_lshl_or_b32 v168, s49, 7, v153
	v_ashrrev_i32_e32 v169, 31, v168
	s_movk_i32 s20, 0x1600
	s_andn2_b64 vcc, exec, s[38:39]
	s_waitcnt vmcnt(0)
	v_add_f32_e32 v170, v170, v171
	v_add_f32_e32 v174, v174, v175
	v_add_f32_e32 v178, v178, v179
	v_add_f32_e32 v182, v182, v183
	v_add_f32_e32 v186, v186, v187
	v_add_f32_e32 v190, v190, v191
	v_add_f32_e32 v204, v204, v205
	v_add_f32_e32 v208, v208, v209
	v_add_f32_e32 v172, v172, v173
	v_add_f32_e32 v176, v176, v177
	v_add_f32_e32 v180, v180, v181
	v_add_f32_e32 v184, v184, v185
	v_add_f32_e32 v188, v188, v189
	v_add_f32_e32 v192, v192, v193
	v_add_f32_e32 v206, v206, v207
	v_add_f32_e32 v210, v210, v211
	v_add_f32_e32 v170, v170, v172
	v_add_f32_e32 v174, v174, v176
	v_add_f32_e32 v178, v178, v180
	v_add_f32_e32 v182, v182, v184
	v_add_f32_e32 v186, v186, v188
	v_add_f32_e32 v190, v190, v192
	v_add_f32_e32 v204, v204, v206
	v_add_f32_e32 v208, v208, v210
	v_fmamk_f32 v170, v170, 0x3a800000, v241
	v_fmamk_f32 v174, v174, 0x3a800000, v241
	v_fmamk_f32 v178, v178, 0x3a800000, v241
	v_fmamk_f32 v182, v182, 0x3a800000, v241
	v_fmamk_f32 v186, v186, 0x3a800000, v241
	v_fmamk_f32 v190, v190, 0x3a800000, v241
	v_fmamk_f32 v204, v204, 0x3a800000, v241
	v_fmamk_f32 v208, v208, 0x3a800000, v241
	v_rsq_f32_e32 v173, v170
	v_rsq_f32_e32 v177, v174
	v_rsq_f32_e32 v181, v178
	v_rsq_f32_e32 v185, v182
	v_rsq_f32_e32 v189, v186
	v_rsq_f32_e32 v193, v190
	v_rsq_f32_e32 v207, v204
	v_rsq_f32_e32 v211, v208
	v_mul_u32_u24_e32 v224, 0x1600, v166
	v_lshl_add_u32 v224, v168, 1, v224
	v_mul_f32_e32 v172, 0xbfb8aa3b, v173
	v_mul_f32_e32 v176, 0xbfb8aa3b, v177
	v_mul_f32_e32 v180, 0xbfb8aa3b, v181
	v_mul_f32_e32 v184, 0xbfb8aa3b, v185
	v_mul_f32_e32 v188, 0xbfb8aa3b, v189
	v_mul_f32_e32 v192, 0xbfb8aa3b, v193
	v_mul_f32_e32 v206, 0xbfb8aa3b, v207
	v_mul_f32_e32 v210, 0xbfb8aa3b, v211
	v_pk_mul_f32 v[216:217], v[126:127], v[172:173] op_sel_hi:[1,0]
	v_pk_mul_f32 v[218:219], v[128:129], v[172:173] op_sel_hi:[1,0]
	v_pk_mul_f32 v[220:221], v[122:123], v[172:173] op_sel_hi:[1,0]
	v_pk_mul_f32 v[222:223], v[124:125], v[172:173] op_sel_hi:[1,0]
	v_pk_mul_f32 v[126:127], v[126:127], v[118:119]
	v_pk_mul_f32 v[128:129], v[128:129], v[120:121]
	v_pk_mul_f32 v[122:123], v[122:123], v[114:115]
	v_pk_mul_f32 v[124:125], v[124:125], v[116:117]
	v_exp_f32_e32 v216, v216
	v_exp_f32_e32 v217, v217
	v_exp_f32_e32 v218, v218
	v_exp_f32_e32 v219, v219
	v_exp_f32_e32 v220, v220
	v_exp_f32_e32 v221, v221
	v_exp_f32_e32 v222, v222
	v_exp_f32_e32 v223, v223
	v_mov_b32_e32 v225, v224
	v_pk_fma_f32 v[216:217], v[216:217], v[170:171], v[170:171] op_sel_hi:[1,0,0]
	v_pk_fma_f32 v[218:219], v[218:219], v[170:171], v[170:171] op_sel_hi:[1,0,0]
	v_pk_fma_f32 v[220:221], v[220:221], v[170:171], v[170:171] op_sel_hi:[1,0,0]
	v_pk_fma_f32 v[222:223], v[222:223], v[170:171], v[170:171] op_sel_hi:[1,0,0]
	v_rcp_f32_e32 v216, v216
	v_rcp_f32_e32 v217, v217
	v_rcp_f32_e32 v218, v218
	v_rcp_f32_e32 v219, v219
	v_rcp_f32_e32 v220, v220
	v_rcp_f32_e32 v221, v221
	v_rcp_f32_e32 v222, v222
	v_rcp_f32_e32 v223, v223
	v_pk_mul_f32 v[126:127], v[126:127], v[216:217]
	v_pk_mul_f32 v[128:129], v[128:129], v[218:219]
	v_pk_mul_f32 v[122:123], v[122:123], v[220:221]
	v_pk_mul_f32 v[124:125], v[124:125], v[222:223]
	s_nop 0
	v_cvt_pk_bf16_f32 v126, v126, v127
	v_cvt_pk_bf16_f32 v127, v128, v129
	v_cvt_pk_bf16_f32 v128, v122, v123
	v_cvt_pk_bf16_f32 v129, v124, v125
	global_store_dwordx4 v225, v[126:129], s[12:13]
	v_pk_mul_f32 v[216:217], v[110:111], v[176:177] op_sel_hi:[1,0]
	v_pk_mul_f32 v[218:219], v[112:113], v[176:177] op_sel_hi:[1,0]
	v_pk_mul_f32 v[220:221], v[106:107], v[176:177] op_sel_hi:[1,0]
	v_pk_mul_f32 v[222:223], v[108:109], v[176:177] op_sel_hi:[1,0]
	v_pk_mul_f32 v[110:111], v[110:111], v[102:103]
	v_pk_mul_f32 v[112:113], v[112:113], v[104:105]
	v_pk_mul_f32 v[106:107], v[106:107], v[98:99]
	v_pk_mul_f32 v[108:109], v[108:109], v[100:101]
	v_exp_f32_e32 v216, v216
	v_exp_f32_e32 v217, v217
	v_exp_f32_e32 v218, v218
	v_exp_f32_e32 v219, v219
	v_exp_f32_e32 v220, v220
	v_exp_f32_e32 v221, v221
	v_exp_f32_e32 v222, v222
	v_exp_f32_e32 v223, v223
	v_add_u32_e32 v225, 0x16000, v224
	v_pk_fma_f32 v[216:217], v[216:217], v[174:175], v[174:175] op_sel_hi:[1,0,0]
	v_pk_fma_f32 v[218:219], v[218:219], v[174:175], v[174:175] op_sel_hi:[1,0,0]
; __device__ __forceinline__ unsigned pk(float lo, float hi) { f32x2v v = {lo, hi}; bf16x2v b = __builtin_convertvector(v, bf16x2v); return __builtin_bit_cast(unsigned, b); }
; __device__ __forceinline__ float silu_f(float x) { return x * __builtin_amdgcn_rcpf(1.0f + __builtin_amdgcn_exp2f(-1.4426950408889634f * x)); }
;     __device__ __forceinline__ void operator()(const f32x4 (&acc)[2][2][4][2], const Unit& u, int wr, int wc, int fr, int fq) const {
;     ...
;             for (int m = 0; m < 4; ++m) { const int row = row0 + ai * HALF + m * 16; const float rs = rsv[ai][m];
;                 const f32x4 g0 = acc[ai][0][m][0] * rs, g1 = acc[ai][0][m][1] * rs, u0 = acc[ai][1][m][0] * rs, u1 = acc[ai][1][m][1] * rs;
;                 u32x4 w; w.x = pk(silu_f(g0[0]) * u0[0], silu_f(g0[1]) * u0[1]); w.y = pk(silu_f(g0[2]) * u0[2], silu_f(g0[3]) * u0[3]);
;                 w.z = pk(silu_f(g1[0]) * u1[0], silu_f(g1[1]) * u1[1]); w.w = pk(silu_f(g1[2]) * u1[2], silu_f(g1[3]) * u1[3]);
;                 *(u32x4*)(H + (size_t)row * DFF + col0) = w; }
	v_pk_fma_f32 v[220:221], v[220:221], v[174:175], v[174:175] op_sel_hi:[1,0,0]
	v_pk_fma_f32 v[222:223], v[222:223], v[174:175], v[174:175] op_sel_hi:[1,0,0]
	v_rcp_f32_e32 v216, v216
	v_rcp_f32_e32 v217, v217
	v_rcp_f32_e32 v218, v218
	v_rcp_f32_e32 v219, v219
	v_rcp_f32_e32 v220, v220
	v_rcp_f32_e32 v221, v221
	v_rcp_f32_e32 v222, v222
	v_rcp_f32_e32 v223, v223
	v_pk_mul_f32 v[110:111], v[110:111], v[216:217]
	v_pk_mul_f32 v[112:113], v[112:113], v[218:219]
	v_pk_mul_f32 v[106:107], v[106:107], v[220:221]
	v_pk_mul_f32 v[108:109], v[108:109], v[222:223]
	s_nop 0
	v_cvt_pk_bf16_f32 v110, v110, v111
	v_cvt_pk_bf16_f32 v111, v112, v113
	v_cvt_pk_bf16_f32 v112, v106, v107
	v_cvt_pk_bf16_f32 v113, v108, v109
	global_store_dwordx4 v225, v[110:113], s[12:13]
	v_pk_mul_f32 v[216:217], v[94:95], v[180:181] op_sel_hi:[1,0]
	v_pk_mul_f32 v[218:219], v[96:97], v[180:181] op_sel_hi:[1,0]
	v_pk_mul_f32 v[220:221], v[90:91], v[180:181] op_sel_hi:[1,0]
	v_pk_mul_f32 v[222:223], v[92:93], v[180:181] op_sel_hi:[1,0]
	v_pk_mul_f32 v[94:95], v[94:95], v[86:87]
	v_pk_mul_f32 v[96:97], v[96:97], v[88:89]
	v_pk_mul_f32 v[90:91], v[90:91], v[82:83]
	v_pk_mul_f32 v[92:93], v[92:93], v[84:85]
	v_exp_f32_e32 v216, v216
	v_exp_f32_e32 v217, v217
	v_exp_f32_e32 v218, v218
	v_exp_f32_e32 v219, v219
	v_exp_f32_e32 v220, v220
	v_exp_f32_e32 v221, v221
	v_exp_f32_e32 v222, v222
	v_exp_f32_e32 v223, v223
	v_add_u32_e32 v225, 0x2c000, v224
	v_pk_fma_f32 v[216:217], v[216:217], v[178:179], v[178:179] op_sel_hi:[1,0,0]
	v_pk_fma_f32 v[218:219], v[218:219], v[178:179], v[178:179] op_sel_hi:[1,0,0]
	v_pk_fma_f32 v[220:221], v[220:221], v[178:179], v[178:179] op_sel_hi:[1,0,0]
	v_pk_fma_f32 v[222:223], v[222:223], v[178:179], v[178:179] op_sel_hi:[1,0,0]
	v_rcp_f32_e32 v216, v216
	v_rcp_f32_e32 v217, v217
	v_rcp_f32_e32 v218, v218
	v_rcp_f32_e32 v219, v219
	v_rcp_f32_e32 v220, v220
	v_rcp_f32_e32 v221, v221
	v_rcp_f32_e32 v222, v222
	v_rcp_f32_e32 v223, v223
	v_pk_mul_f32 v[94:95], v[94:95], v[216:217]
	v_pk_mul_f32 v[96:97], v[96:97], v[218:219]
	v_pk_mul_f32 v[90:91], v[90:91], v[220:221]
	v_pk_mul_f32 v[92:93], v[92:93], v[222:223]
	s_nop 0
	v_cvt_pk_bf16_f32 v94, v94, v95
	v_cvt_pk_bf16_f32 v95, v96, v97
	v_cvt_pk_bf16_f32 v96, v90, v91
	v_cvt_pk_bf16_f32 v97, v92, v93
	global_store_dwordx4 v225, v[94:97], s[12:13]
	v_pk_mul_f32 v[216:217], v[78:79], v[184:185] op_sel_hi:[1,0]
	v_pk_mul_f32 v[218:219], v[80:81], v[184:185] op_sel_hi:[1,0]
	v_pk_mul_f32 v[220:221], v[74:75], v[184:185] op_sel_hi:[1,0]
	v_pk_mul_f32 v[222:223], v[76:77], v[184:185] op_sel_hi:[1,0]
	v_pk_mul_f32 v[78:79], v[78:79], v[70:71]
	v_pk_mul_f32 v[80:81], v[80:81], v[72:73]
	v_pk_mul_f32 v[74:75], v[74:75], v[66:67]
	v_pk_mul_f32 v[76:77], v[76:77], v[68:69]
	v_exp_f32_e32 v216, v216
	v_exp_f32_e32 v217, v217
	v_exp_f32_e32 v218, v218
	v_exp_f32_e32 v219, v219
	v_exp_f32_e32 v220, v220
	v_exp_f32_e32 v221, v221
	v_exp_f32_e32 v222, v222
	v_exp_f32_e32 v223, v223
	v_add_u32_e32 v225, 0x42000, v224
	v_pk_fma_f32 v[216:217], v[216:217], v[182:183], v[182:183] op_sel_hi:[1,0,0]
	v_pk_fma_f32 v[218:219], v[218:219], v[182:183], v[182:183] op_sel_hi:[1,0,0]
	v_pk_fma_f32 v[220:221], v[220:221], v[182:183], v[182:183] op_sel_hi:[1,0,0]
	v_pk_fma_f32 v[222:223], v[222:223], v[182:183], v[182:183] op_sel_hi:[1,0,0]
	v_rcp_f32_e32 v216, v216
	v_rcp_f32_e32 v217, v217
	v_rcp_f32_e32 v218, v218
	v_rcp_f32_e32 v219, v219
	v_rcp_f32_e32 v220, v220
	v_rcp_f32_e32 v221, v221
	v_rcp_f32_e32 v222, v222
	v_rcp_f32_e32 v223, v223
	v_pk_mul_f32 v[78:79], v[78:79], v[216:217]
	v_pk_mul_f32 v[80:81], v[80:81], v[218:219]
	v_pk_mul_f32 v[74:75], v[74:75], v[220:221]
	v_pk_mul_f32 v[76:77], v[76:77], v[222:223]
	s_nop 0
	v_cvt_pk_bf16_f32 v78, v78, v79
	v_cvt_pk_bf16_f32 v79, v80, v81
	v_cvt_pk_bf16_f32 v80, v74, v75
	v_cvt_pk_bf16_f32 v81, v76, v77
	global_store_dwordx4 v225, v[78:81], s[12:13]
	v_pk_mul_f32 v[216:217], v[62:63], v[188:189] op_sel_hi:[1,0]
	v_pk_mul_f32 v[218:219], v[64:65], v[188:189] op_sel_hi:[1,0]
	v_pk_mul_f32 v[220:221], v[58:59], v[188:189] op_sel_hi:[1,0]
	v_pk_mul_f32 v[222:223], v[60:61], v[188:189] op_sel_hi:[1,0]
	v_pk_mul_f32 v[62:63], v[62:63], v[54:55]
	v_pk_mul_f32 v[64:65], v[64:65], v[56:57]
	v_pk_mul_f32 v[58:59], v[58:59], v[50:51]
	v_pk_mul_f32 v[60:61], v[60:61], v[52:53]
	v_exp_f32_e32 v216, v216
	v_exp_f32_e32 v217, v217
	v_exp_f32_e32 v218, v218
	v_exp_f32_e32 v219, v219
	v_exp_f32_e32 v220, v220
	v_exp_f32_e32 v221, v221
	v_exp_f32_e32 v222, v222
	v_exp_f32_e32 v223, v223
	v_add_u32_e32 v225, 0xb0000, v224
	v_pk_fma_f32 v[216:217], v[216:217], v[186:187], v[186:187] op_sel_hi:[1,0,0]
	v_pk_fma_f32 v[218:219], v[218:219], v[186:187], v[186:187] op_sel_hi:[1,0,0]
	v_pk_fma_f32 v[220:221], v[220:221], v[186:187], v[186:187] op_sel_hi:[1,0,0]
	v_pk_fma_f32 v[222:223], v[222:223], v[186:187], v[186:187] op_sel_hi:[1,0,0]
	v_rcp_f32_e32 v216, v216
	v_rcp_f32_e32 v217, v217
	v_rcp_f32_e32 v218, v218
	v_rcp_f32_e32 v219, v219
	v_rcp_f32_e32 v220, v220
	v_rcp_f32_e32 v221, v221
	v_rcp_f32_e32 v222, v222
	v_rcp_f32_e32 v223, v223
	v_pk_mul_f32 v[62:63], v[62:63], v[216:217]
; __device__ __forceinline__ unsigned pk(float lo, float hi) { f32x2v v = {lo, hi}; bf16x2v b = __builtin_convertvector(v, bf16x2v); return __builtin_bit_cast(unsigned, b); }
; __device__ __forceinline__ float silu_f(float x) { return x * __builtin_amdgcn_rcpf(1.0f + __builtin_amdgcn_exp2f(-1.4426950408889634f * x)); }
;     __device__ __forceinline__ void operator()(const f32x4 (&acc)[2][2][4][2], const Unit& u, int wr, int wc, int fr, int fq) const {
;     ...
;             for (int m = 0; m < 4; ++m) { const int row = row0 + ai * HALF + m * 16; const float rs = rsv[ai][m];
;                 const f32x4 g0 = acc[ai][0][m][0] * rs, g1 = acc[ai][0][m][1] * rs, u0 = acc[ai][1][m][0] * rs, u1 = acc[ai][1][m][1] * rs;
;                 u32x4 w; w.x = pk(silu_f(g0[0]) * u0[0], silu_f(g0[1]) * u0[1]); w.y = pk(silu_f(g0[2]) * u0[2], silu_f(g0[3]) * u0[3]);
;                 w.z = pk(silu_f(g1[0]) * u1[0], silu_f(g1[1]) * u1[1]); w.w = pk(silu_f(g1[2]) * u1[2], silu_f(g1[3]) * u1[3]);
;                 *(u32x4*)(H + (size_t)row * DFF + col0) = w; }
	v_pk_mul_f32 v[64:65], v[64:65], v[218:219]
	v_pk_mul_f32 v[58:59], v[58:59], v[220:221]
	v_pk_mul_f32 v[60:61], v[60:61], v[222:223]
	s_nop 0
	v_cvt_pk_bf16_f32 v62, v62, v63
	v_cvt_pk_bf16_f32 v63, v64, v65
	v_cvt_pk_bf16_f32 v64, v58, v59
	v_cvt_pk_bf16_f32 v65, v60, v61
	global_store_dwordx4 v225, v[62:65], s[12:13]
	v_pk_mul_f32 v[216:217], v[46:47], v[192:193] op_sel_hi:[1,0]
	v_pk_mul_f32 v[218:219], v[48:49], v[192:193] op_sel_hi:[1,0]
	v_pk_mul_f32 v[220:221], v[42:43], v[192:193] op_sel_hi:[1,0]
	v_pk_mul_f32 v[222:223], v[44:45], v[192:193] op_sel_hi:[1,0]
	v_pk_mul_f32 v[46:47], v[46:47], v[38:39]
	v_pk_mul_f32 v[48:49], v[48:49], v[40:41]
	v_pk_mul_f32 v[42:43], v[42:43], v[34:35]
	v_pk_mul_f32 v[44:45], v[44:45], v[36:37]
	v_exp_f32_e32 v216, v216
	v_exp_f32_e32 v217, v217
	v_exp_f32_e32 v218, v218
	v_exp_f32_e32 v219, v219
	v_exp_f32_e32 v220, v220
	v_exp_f32_e32 v221, v221
	v_exp_f32_e32 v222, v222
	v_exp_f32_e32 v223, v223
	v_add_u32_e32 v225, 0xc6000, v224
	v_pk_fma_f32 v[216:217], v[216:217], v[190:191], v[190:191] op_sel_hi:[1,0,0]
	v_pk_fma_f32 v[218:219], v[218:219], v[190:191], v[190:191] op_sel_hi:[1,0,0]
	v_pk_fma_f32 v[220:221], v[220:221], v[190:191], v[190:191] op_sel_hi:[1,0,0]
	v_pk_fma_f32 v[222:223], v[222:223], v[190:191], v[190:191] op_sel_hi:[1,0,0]
	v_rcp_f32_e32 v216, v216
	v_rcp_f32_e32 v217, v217
	v_rcp_f32_e32 v218, v218
	v_rcp_f32_e32 v219, v219
	v_rcp_f32_e32 v220, v220
	v_rcp_f32_e32 v221, v221
	v_rcp_f32_e32 v222, v222
	v_rcp_f32_e32 v223, v223
	v_pk_mul_f32 v[46:47], v[46:47], v[216:217]
	v_pk_mul_f32 v[48:49], v[48:49], v[218:219]
	v_pk_mul_f32 v[42:43], v[42:43], v[220:221]
	v_pk_mul_f32 v[44:45], v[44:45], v[222:223]
	s_nop 0
	v_cvt_pk_bf16_f32 v46, v46, v47
	v_cvt_pk_bf16_f32 v47, v48, v49
	v_cvt_pk_bf16_f32 v48, v42, v43
	v_cvt_pk_bf16_f32 v49, v44, v45
	global_store_dwordx4 v225, v[46:49], s[12:13]
	v_pk_mul_f32 v[216:217], v[30:31], v[206:207] op_sel_hi:[1,0]
	v_pk_mul_f32 v[218:219], v[32:33], v[206:207] op_sel_hi:[1,0]
	v_pk_mul_f32 v[220:221], v[26:27], v[206:207] op_sel_hi:[1,0]
	v_pk_mul_f32 v[222:223], v[28:29], v[206:207] op_sel_hi:[1,0]
	v_pk_mul_f32 v[30:31], v[30:31], v[22:23]
	v_pk_mul_f32 v[32:33], v[32:33], v[24:25]
	v_pk_mul_f32 v[26:27], v[26:27], v[18:19]
	v_pk_mul_f32 v[28:29], v[28:29], v[20:21]
	v_exp_f32_e32 v216, v216
	v_exp_f32_e32 v217, v217
	v_exp_f32_e32 v218, v218
	v_exp_f32_e32 v219, v219
	v_exp_f32_e32 v220, v220
	v_exp_f32_e32 v221, v221
	v_exp_f32_e32 v222, v222
	v_exp_f32_e32 v223, v223
	v_add_u32_e32 v225, 0xdc000, v224
	v_pk_fma_f32 v[216:217], v[216:217], v[204:205], v[204:205] op_sel_hi:[1,0,0]
	v_pk_fma_f32 v[218:219], v[218:219], v[204:205], v[204:205] op_sel_hi:[1,0,0]
	v_pk_fma_f32 v[220:221], v[220:221], v[204:205], v[204:205] op_sel_hi:[1,0,0]
	v_pk_fma_f32 v[222:223], v[222:223], v[204:205], v[204:205] op_sel_hi:[1,0,0]
	v_rcp_f32_e32 v216, v216
	v_rcp_f32_e32 v217, v217
	v_rcp_f32_e32 v218, v218
	v_rcp_f32_e32 v219, v219
	v_rcp_f32_e32 v220, v220
	v_rcp_f32_e32 v221, v221
	v_rcp_f32_e32 v222, v222
	v_rcp_f32_e32 v223, v223
	v_pk_mul_f32 v[30:31], v[30:31], v[216:217]
	v_pk_mul_f32 v[32:33], v[32:33], v[218:219]
	v_pk_mul_f32 v[26:27], v[26:27], v[220:221]
	v_pk_mul_f32 v[28:29], v[28:29], v[222:223]
	s_nop 0
	v_cvt_pk_bf16_f32 v30, v30, v31
	v_cvt_pk_bf16_f32 v31, v32, v33
	v_cvt_pk_bf16_f32 v32, v26, v27
	v_cvt_pk_bf16_f32 v33, v28, v29
	global_store_dwordx4 v225, v[30:33], s[12:13]
	v_pk_mul_f32 v[216:217], v[14:15], v[210:211] op_sel_hi:[1,0]
	v_pk_mul_f32 v[218:219], v[16:17], v[210:211] op_sel_hi:[1,0]
	v_pk_mul_f32 v[220:221], v[10:11], v[210:211] op_sel_hi:[1,0]
	v_pk_mul_f32 v[222:223], v[12:13], v[210:211] op_sel_hi:[1,0]
	v_pk_mul_f32 v[14:15], v[14:15], v[6:7]
	v_pk_mul_f32 v[16:17], v[16:17], v[8:9]
	v_pk_mul_f32 v[10:11], v[10:11], v[2:3]
	v_pk_mul_f32 v[12:13], v[12:13], v[4:5]
	v_exp_f32_e32 v216, v216
	v_exp_f32_e32 v217, v217
	v_exp_f32_e32 v218, v218
	v_exp_f32_e32 v219, v219
	v_exp_f32_e32 v220, v220
	v_exp_f32_e32 v221, v221
	v_exp_f32_e32 v222, v222
	v_exp_f32_e32 v223, v223
	v_add_u32_e32 v225, 0xf2000, v224
	v_pk_fma_f32 v[216:217], v[216:217], v[208:209], v[208:209] op_sel_hi:[1,0,0]
	v_pk_fma_f32 v[218:219], v[218:219], v[208:209], v[208:209] op_sel_hi:[1,0,0]
	v_pk_fma_f32 v[220:221], v[220:221], v[208:209], v[208:209] op_sel_hi:[1,0,0]
	v_pk_fma_f32 v[222:223], v[222:223], v[208:209], v[208:209] op_sel_hi:[1,0,0]
	v_rcp_f32_e32 v216, v216
	v_rcp_f32_e32 v217, v217
	v_rcp_f32_e32 v218, v218
	v_rcp_f32_e32 v219, v219
	v_rcp_f32_e32 v220, v220
	v_rcp_f32_e32 v221, v221
	v_rcp_f32_e32 v222, v222
	v_rcp_f32_e32 v223, v223
	v_pk_mul_f32 v[14:15], v[14:15], v[216:217]
	v_pk_mul_f32 v[16:17], v[16:17], v[218:219]
	v_pk_mul_f32 v[10:11], v[10:11], v[220:221]
	v_pk_mul_f32 v[12:13], v[12:13], v[222:223]
	s_nop 0
	v_cvt_pk_bf16_f32 v14, v14, v15
	v_cvt_pk_bf16_f32 v15, v16, v17
	v_cvt_pk_bf16_f32 v16, v10, v11
	v_cvt_pk_bf16_f32 v17, v12, v13
	global_store_dwordx4 v225, v[14:17], s[12:13]
	s_mov_b64 s[8:9], -1
	s_cbranch_vccnz .LBB0_313
	s_andn2_b64 vcc, exec, s[4:5]
	s_cbranch_vccnz .LBB0_312
	s_barrier
	s_branch .LBB0_312
